# v013 variant: attention K/V LDS commit moved to the start of the fast tail (before the P.V reads)
# baseline (speedup 1.0000x reference)
; #define LAS __attribute__((address_space(3)))
; #define MFMA16(a, b, c) __builtin_amdgcn_mfma_f32_16x16x32_bf16((a), (b), (c), 0, 0, 0)
; DI u32x2 tr4(const LAS unsigned char* p) { return __builtin_bit_cast(u32x2, __builtin_amdgcn_ds_read_tr16_b64_v4i16((LAS v4i16_t*)p)); }
; DI bf16x8 packp(f32x4 a, f32x4 b) { return __builtin_bit_cast(bf16x8, pack8(a, b)); }
; DI void atb_commit(const AtRawB& r, LAS unsigned char* buf, int tid) {
; #pragma unroll
;     for (int c = 0; c < 2; ++c) { const int e = tid + c * NTHR, key = e >> 4, c8 = (e & 15) * 8;
;         *(LAS u32x4*)(buf + AT_K + key * 272 + c8 * 2) = r.k[c]; *(LAS u32x4*)(buf + AT_V + key * 288 + c8 * 2) = r.v[c]; }
; }
; DI void at_pv(AtState& S, const f32x4 (&s1)[4], const f32x4 (&s2)[4], float alpha, float ps1, float ps2, const LAS unsigned char* buf, int hh, int fq, int tq, int tp) {
;     S.l1 = S.l1 * alpha + ps1; S.l2 = S.l2 * alpha + ps2;
; #pragma unroll
;     for (int dt = 0; dt < 4; ++dt) { S.O1[dt] = S.O1[dt] * alpha; S.O2[dt] = S.O2[dt] * alpha; }
;     bf16x8 p1[2], p2[2];
; #pragma unroll
;     for (int s = 0; s < 2; ++s) { p1[s] = packp(s1[2 * s], s1[2 * s + 1]); p2[s] = packp(s2[2 * s], s2[2 * s + 1]); }
; #pragma unroll
;     for (int dh = 0; dh < 2; ++dh) {
;         bf16x8 vt[2][2];
; #pragma unroll
;         for (int d2 = 0; d2 < 2; ++d2)
; #pragma unroll
;             for (int s = 0; s < 2; ++s) { const int dt = 2 * dh + d2; const LAS unsigned char* vr = buf + AT_V + (32 * s + 4 * fq + tq) * 288 + (hh * 64 + 16 * dt + 4 * tp) * 2; vt[d2][s] = cat44(tr4(vr), tr4(vr + 16 * 288)); }
;         __builtin_amdgcn_s_setprio(1);
; #pragma unroll
;         for (int s = 0; s < 2; ++s)
; #pragma unroll
;             for (int d2 = 0; d2 < 2; ++d2) { const int dt = 2 * dh + d2; S.O1[dt] = MFMA16(vt[d2][s], p1[s], S.O1[dt]); S.O2[dt] = MFMA16(vt[d2][s], p2[s], S.O2[dt]); }
;         __builtin_amdgcn_s_setprio(0);
;         __builtin_amdgcn_sched_barrier(0);
;     }
.LBB0_1379:
	s_waitcnt vmcnt(4)
	ds_write_b128 v143, v[12:15] offset:35840
	ds_write_b128 v202, v[16:19] offset:53248
	ds_write_b128 v203, v[20:23] offset:35840
	ds_write_b128 v204, v[24:27] offset:53248
	v_cvt_pk_bf16_f32 v216, v164, v165
	v_cvt_pk_bf16_f32 v219, v176, v177
	v_cvt_pk_bf16_f32 v165, v174, v175
	ds_read_b64_tr_b16 v[108:109], v208 offset:17408
	ds_read_b64_tr_b16 v[112:113], v208 offset:17440
	ds_read_b64_tr_b16 v[110:111], v208 offset:22016
	ds_read_b64_tr_b16 v[116:117], v208 offset:26624
	ds_read_b64_tr_b16 v[118:119], v208 offset:31232
	ds_read_b64_tr_b16 v[114:115], v208 offset:22048
	ds_read_b64_tr_b16 v[174:175], v208 offset:26656
	ds_read_b64_tr_b16 v[176:177], v208 offset:31264
	v_mov_b32_e32 v151, v150
	v_pk_fma_f32 v[158:159], v[154:155], v[156:157], v[194:195]
	v_pk_mul_f32 v[78:79], v[150:151], v[66:67]
	v_pk_mul_f32 v[76:77], v[152:153], v[64:65]
	v_pk_mul_f32 v[82:83], v[150:151], v[74:75]
	v_pk_mul_f32 v[80:81], v[152:153], v[72:73]
	v_pk_mul_f32 v[98:99], v[150:151], v[62:63]
	v_pk_mul_f32 v[96:97], v[152:153], v[60:61]
	v_pk_mul_f32 v[106:107], v[150:151], v[70:71]
	v_pk_mul_f32 v[104:105], v[152:153], v[68:69]
	v_pk_mul_f32 v[126:127], v[150:151], v[90:91]
	v_pk_mul_f32 v[124:125], v[152:153], v[88:89]
	v_pk_mul_f32 v[130:131], v[150:151], v[102:103]
	v_pk_mul_f32 v[128:129], v[152:153], v[100:101]
	v_pk_mul_f32 v[134:135], v[150:151], v[86:87]
	v_pk_mul_f32 v[132:133], v[152:153], v[84:85]
	v_pk_mul_f32 v[138:139], v[150:151], v[94:95]
	v_pk_mul_f32 v[136:137], v[152:153], v[92:93]
	v_cvt_pk_bf16_f32 v217, v168, v169
	v_cvt_pk_bf16_f32 v218, v172, v173
	v_cvt_pk_bf16_f32 v162, v162, v163
	v_cvt_pk_bf16_f32 v163, v166, v167
	v_cvt_pk_bf16_f32 v164, v170, v171
	v_cvt_pk_bf16_f32 v166, v180, v181
	v_cvt_pk_bf16_f32 v167, v184, v185
	v_cvt_pk_bf16_f32 v168, v188, v189
	v_cvt_pk_bf16_f32 v169, v192, v193
	v_cvt_pk_bf16_f32 v170, v178, v179
	v_cvt_pk_bf16_f32 v171, v182, v183
	v_cvt_pk_bf16_f32 v172, v186, v187
	v_cvt_pk_bf16_f32 v173, v190, v191
	s_setprio 1
	s_waitcnt lgkmcnt(5)
	v_mfma_f32_16x16x32_bf16 v[76:79], v[108:111], v[216:219], v[76:79]
	v_mfma_f32_16x16x32_bf16 v[80:83], v[108:111], v[162:165], v[80:83]
	s_waitcnt lgkmcnt(2)
	v_mfma_f32_16x16x32_bf16 v[96:99], v[112:115], v[216:219], v[96:99]
	v_mfma_f32_16x16x32_bf16 v[104:107], v[112:115], v[162:165], v[104:107]
	v_mfma_f32_16x16x32_bf16 v[120:123], v[116:119], v[166:169], v[76:79]
	v_mfma_f32_16x16x32_bf16 v[116:119], v[116:119], v[170:173], v[80:83]
	s_waitcnt lgkmcnt(0)
	v_mfma_f32_16x16x32_bf16 v[112:115], v[174:177], v[166:169], v[96:99]
	v_mfma_f32_16x16x32_bf16 v[108:111], v[174:177], v[170:173], v[104:107]
	s_setprio 0
	ds_read_b64_tr_b16 v[76:77], v208 offset:17472
	ds_read_b64_tr_b16 v[80:81], v208 offset:17504
	ds_read_b64_tr_b16 v[78:79], v208 offset:22080
	ds_read_b64_tr_b16 v[82:83], v208 offset:22112
	ds_read_b64_tr_b16 v[96:97], v208 offset:26688
	ds_read_b64_tr_b16 v[98:99], v208 offset:31296
	ds_read_b64_tr_b16 v[106:107], v208 offset:31328
	ds_read_b64_tr_b16 v[104:105], v208 offset:26720
	s_setprio 1
	s_waitcnt lgkmcnt(5)
	v_mfma_f32_16x16x32_bf16 v[124:127], v[76:79], v[216:219], v[124:127]
	v_mfma_f32_16x16x32_bf16 v[76:79], v[76:79], v[162:165], v[128:131]
	s_waitcnt lgkmcnt(4)
	v_mfma_f32_16x16x32_bf16 v[128:131], v[80:83], v[216:219], v[132:135]
	v_mfma_f32_16x16x32_bf16 v[80:83], v[80:83], v[162:165], v[136:139]
	s_waitcnt lgkmcnt(2)
	v_mfma_f32_16x16x32_bf16 v[136:139], v[96:99], v[166:169], v[124:127]
	v_mfma_f32_16x16x32_bf16 v[132:135], v[96:99], v[170:173], v[76:79]
	s_waitcnt lgkmcnt(0)
	v_mfma_f32_16x16x32_bf16 v[128:131], v[104:107], v[166:169], v[128:131]
	v_mfma_f32_16x16x32_bf16 v[124:127], v[104:107], v[170:173], v[80:83]
	s_setprio 0
	s_nop 1
	v_mov_b64_e32 v[82:83], v[58:59]
	v_mov_b64_e32 v[78:79], v[46:47]
	v_mov_b64_e32 v[98:99], v[50:51]
	v_mov_b64_e32 v[106:107], v[54:55]
	v_mov_b32_e32 v3, v215
	v_mov_b64_e32 v[80:81], v[56:57]
	v_mov_b64_e32 v[76:77], v[44:45]
	v_mov_b64_e32 v[96:97], v[48:49]
	v_mov_b64_e32 v[104:105], v[52:53]
	s_mov_b64 s[18:19], 0
	s_branch .Lcommit_done_A

; #define LAS __attribute__((address_space(3)))
; #define MFMA16(a, b, c) __builtin_amdgcn_mfma_f32_16x16x32_bf16((a), (b), (c), 0, 0, 0)
; DI u32x2 tr4(const LAS unsigned char* p) { return __builtin_bit_cast(u32x2, __builtin_amdgcn_ds_read_tr16_b64_v4i16((LAS v4i16_t*)p)); }
; DI bf16x8 packp(f32x4 a, f32x4 b) { return __builtin_bit_cast(bf16x8, pack8(a, b)); }
; DI void atb_commit(const AtRawB& r, LAS unsigned char* buf, int tid) {
; #pragma unroll
;     for (int c = 0; c < 2; ++c) { const int e = tid + c * NTHR, key = e >> 4, c8 = (e & 15) * 8;
;         *(LAS u32x4*)(buf + AT_K + key * 272 + c8 * 2) = r.k[c]; *(LAS u32x4*)(buf + AT_V + key * 288 + c8 * 2) = r.v[c]; }
; }
; DI void at_pv(AtState& S, const f32x4 (&s1)[4], const f32x4 (&s2)[4], float alpha, float ps1, float ps2, const LAS unsigned char* buf, int hh, int fq, int tq, int tp) {
;     S.l1 = S.l1 * alpha + ps1; S.l2 = S.l2 * alpha + ps2;
; #pragma unroll
;     for (int dt = 0; dt < 4; ++dt) { S.O1[dt] = S.O1[dt] * alpha; S.O2[dt] = S.O2[dt] * alpha; }
;     bf16x8 p1[2], p2[2];
; #pragma unroll
;     for (int s = 0; s < 2; ++s) { p1[s] = packp(s1[2 * s], s1[2 * s + 1]); p2[s] = packp(s2[2 * s], s2[2 * s + 1]); }
; #pragma unroll
;     for (int dh = 0; dh < 2; ++dh) {
;         bf16x8 vt[2][2];
; #pragma unroll
;         for (int d2 = 0; d2 < 2; ++d2)
; #pragma unroll
;             for (int s = 0; s < 2; ++s) { const int dt = 2 * dh + d2; const LAS unsigned char* vr = buf + AT_V + (32 * s + 4 * fq + tq) * 288 + (hh * 64 + 16 * dt + 4 * tp) * 2; vt[d2][s] = cat44(tr4(vr), tr4(vr + 16 * 288)); }
;         __builtin_amdgcn_s_setprio(1);
; #pragma unroll
;         for (int s = 0; s < 2; ++s)
; #pragma unroll
;             for (int d2 = 0; d2 < 2; ++d2) { const int dt = 2 * dh + d2; S.O1[dt] = MFMA16(vt[d2][s], p1[s], S.O1[dt]); S.O2[dt] = MFMA16(vt[d2][s], p2[s], S.O2[dt]); }
;         __builtin_amdgcn_s_setprio(0);
;         __builtin_amdgcn_sched_barrier(0);
;     }
.LBB0_1389:
	s_waitcnt vmcnt(4)
	ds_write_b128 v143, v[28:31]
	ds_write_b128 v202, v[32:35] offset:17408
	ds_write_b128 v203, v[36:39]
	ds_write_b128 v204, v[40:43] offset:17408
	s_nop 0
	v_cvt_pk_bf16_f32 v216, v164, v165
	v_cvt_pk_bf16_f32 v219, v176, v177
	v_cvt_pk_bf16_f32 v165, v174, v175
	ds_read_b64_tr_b16 v[60:61], v208 offset:53248
	ds_read_b64_tr_b16 v[64:65], v208 offset:53280
	ds_read_b64_tr_b16 v[62:63], v208 offset:57856
	ds_read_b64_tr_b16 v[68:69], v208 offset:62464
	ds_read_b64_tr_b16 v[70:71], v209 offset:4608
	ds_read_b64_tr_b16 v[66:67], v208 offset:57888
	ds_read_b64_tr_b16 v[174:175], v208 offset:62496
	ds_read_b64_tr_b16 v[176:177], v210 offset:4608
	v_mov_b32_e32 v151, v150
	v_pk_fma_f32 v[156:157], v[154:155], v[158:159], v[194:195]
	v_pk_mul_f32 v[46:47], v[150:151], v[122:123]
	v_pk_mul_f32 v[44:45], v[152:153], v[120:121]
	v_pk_mul_f32 v[50:51], v[150:151], v[118:119]
	v_pk_mul_f32 v[48:49], v[152:153], v[116:117]
	v_pk_mul_f32 v[54:55], v[150:151], v[114:115]
	v_pk_mul_f32 v[52:53], v[152:153], v[112:113]
	v_pk_mul_f32 v[58:59], v[150:151], v[110:111]
	v_pk_mul_f32 v[56:57], v[152:153], v[108:109]
	v_pk_mul_f32 v[86:87], v[150:151], v[138:139]
	v_pk_mul_f32 v[84:85], v[152:153], v[136:137]
	v_pk_mul_f32 v[90:91], v[150:151], v[134:135]
	v_pk_mul_f32 v[88:89], v[152:153], v[132:133]
	v_pk_mul_f32 v[94:95], v[150:151], v[130:131]
	v_pk_mul_f32 v[92:93], v[152:153], v[128:129]
	v_pk_mul_f32 v[102:103], v[150:151], v[126:127]
	v_pk_mul_f32 v[100:101], v[152:153], v[124:125]
	v_cvt_pk_bf16_f32 v217, v168, v169
	v_cvt_pk_bf16_f32 v218, v172, v173
	v_cvt_pk_bf16_f32 v162, v162, v163
	v_cvt_pk_bf16_f32 v163, v166, v167
	v_cvt_pk_bf16_f32 v164, v170, v171
	v_cvt_pk_bf16_f32 v166, v180, v181
	v_cvt_pk_bf16_f32 v167, v184, v185
	v_cvt_pk_bf16_f32 v168, v188, v189
	v_cvt_pk_bf16_f32 v169, v192, v193
	v_cvt_pk_bf16_f32 v170, v178, v179
	v_cvt_pk_bf16_f32 v171, v182, v183
	v_cvt_pk_bf16_f32 v172, v186, v187
	v_cvt_pk_bf16_f32 v173, v190, v191
	s_setprio 1
	s_waitcnt lgkmcnt(5)
	v_mfma_f32_16x16x32_bf16 v[44:47], v[60:63], v[216:219], v[44:47]
	v_mfma_f32_16x16x32_bf16 v[48:51], v[60:63], v[162:165], v[48:51]
	s_waitcnt lgkmcnt(2)
	v_mfma_f32_16x16x32_bf16 v[52:55], v[64:67], v[216:219], v[52:55]
	v_mfma_f32_16x16x32_bf16 v[56:59], v[64:67], v[162:165], v[56:59]
	v_mfma_f32_16x16x32_bf16 v[64:67], v[68:71], v[166:169], v[44:47]
	v_mfma_f32_16x16x32_bf16 v[72:75], v[68:71], v[170:173], v[48:51]
	s_waitcnt lgkmcnt(0)
	v_mfma_f32_16x16x32_bf16 v[60:63], v[174:177], v[166:169], v[52:55]
	v_mfma_f32_16x16x32_bf16 v[68:71], v[174:177], v[170:173], v[56:59]
	s_setprio 0
	ds_read_b64_tr_b16 v[44:45], v208 offset:53312
	ds_read_b64_tr_b16 v[48:49], v208 offset:53344
	ds_read_b64_tr_b16 v[46:47], v208 offset:57920
	ds_read_b64_tr_b16 v[50:51], v208 offset:57952
	ds_read_b64_tr_b16 v[52:53], v208 offset:62528
	ds_read_b64_tr_b16 v[54:55], v211 offset:4608
	ds_read_b64_tr_b16 v[58:59], v212 offset:4608
	ds_read_b64_tr_b16 v[56:57], v208 offset:62560
	s_setprio 1
	s_waitcnt lgkmcnt(5)
	v_mfma_f32_16x16x32_bf16 v[84:87], v[44:47], v[216:219], v[84:87]
	v_mfma_f32_16x16x32_bf16 v[44:47], v[44:47], v[162:165], v[88:91]
	s_waitcnt lgkmcnt(4)
	v_mfma_f32_16x16x32_bf16 v[92:95], v[48:51], v[216:219], v[92:95]
	v_mfma_f32_16x16x32_bf16 v[48:51], v[48:51], v[162:165], v[100:103]
	s_waitcnt lgkmcnt(2)
	v_mfma_f32_16x16x32_bf16 v[88:91], v[52:55], v[166:169], v[84:87]
	v_mfma_f32_16x16x32_bf16 v[100:103], v[52:55], v[170:173], v[44:47]
	s_waitcnt lgkmcnt(0)
	v_mfma_f32_16x16x32_bf16 v[84:87], v[56:59], v[166:169], v[92:95]
	v_mfma_f32_16x16x32_bf16 v[92:95], v[56:59], v[170:173], v[48:51]
	s_setprio 0
	v_mov_b64_e32 v[56:57], v[80:81]
	v_mov_b64_e32 v[44:45], v[76:77]
	v_mov_b64_e32 v[48:49], v[96:97]
	v_mov_b64_e32 v[52:53], v[104:105]
	v_mov_b32_e32 v214, v215
	v_mov_b64_e32 v[58:59], v[82:83]
	v_mov_b64_e32 v[46:47], v[78:79]
	v_mov_b64_e32 v[50:51], v[98:99]
	v_mov_b64_e32 v[54:55], v[106:107]
	s_mov_b64 s[14:15], 0
	s_branch .Lcommit_done_B
